# gdn_intra step0: both kernarg pointer loads issued together and both scalar value loads batched (one fewer SMEM round trip pair on wave-0 path)
# speedup vs baseline: 1.0012x; 1.0012x over previous
; DI void gdn_intra(LAS unsigned char* lds, PP p, int l, int first, int stride) {
;     ...
;     if (tid < 64) {
;         const float bl = LG0, al = LG1;
;         const float beta = 1.f / (1.f + __expf(-bl));
;         const float xx = al + p->in[17][l * 8 + hd];
;         const float ex = __expf(fminf(xx, 20.f));
;         const float sp = xx > 20.f ? xx : (ex < 0.05f ? ex * (1.f - ex * (0.5f - ex * (0.33333333f - ex * 0.25f))) : __logf(1.f + ex));
;         float gc = -__expf(p->in[16][l * 8 + hd]) * sp;
.LBB0_421:
	v_mov_b32_e32 v138, v201
	s_ashr_i32 s55, s54, 31
	v_add_u32_e32 v0, 0x21000, v132
	v_add_u32_e32 v23, 0x20c00, v132
	v_add_u32_e32 v35, 0x20e00, v132
	v_lshl_add_u32 v1, v138, 2, v0
	v_add_u32_e32 v22, 0x20d00, v132
	v_add_u32_e32 v30, 0x20f00, v132
	v_cmp_gt_i32_e64 s[22:23], 64, v138
	s_waitcnt vmcnt(0)
	ds_write2st64_b32 v1, v133, v136 offset1:8
	ds_write_b32 v1, v137 offset:4096
	s_and_saveexec_b64 s[2:3], s[22:23]
	s_cbranch_execz .LBB0_430
	s_load_dwordx2 s[24:25], s[0:1], 0x88
	s_load_dwordx2 s[30:31], s[0:1], 0x80
	s_ashr_i32 s20, s54, 8
	s_add_i32 s20, s20, s65
	s_ashr_i32 s21, s20, 31
	s_lshl_b64 s[20:21], s[20:21], 2
	s_waitcnt lgkmcnt(0)
	s_add_u32 s24, s24, s20
	s_addc_u32 s25, s25, s21
	s_add_u32 s30, s30, s20
	s_addc_u32 s31, s31, s21
	s_load_dword s26, s[24:25], 0x0
	s_load_dword s21, s[30:31], 0x0
	s_waitcnt vmcnt(6) lgkmcnt(0)
	s_mov_b32 s24, 0x41a00000
	v_add_f32_e32 v1, s26, v134
	v_cmp_nlt_f32_e32 vcc, s24, v1
	s_and_saveexec_b64 s[26:27], vcc
	s_cbranch_execz .LBB0_428
	v_max_f32_e32 v1, v1, v1
	v_min_f32_e32 v1, 0x41a00000, v1
	v_mul_f32_e32 v1, 0x3fb8aa3b, v1
	v_exp_f32_e32 v2, v1
	s_mov_b32 s24, 0x3d4ccccd
	v_cmp_ngt_f32_e32 vcc, s24, v2
	s_and_saveexec_b64 s[24:25], vcc
	s_xor_b64 s[28:29], exec, s[24:25]
	s_cbranch_execz .LBB0_425
	v_add_f32_e32 v1, 1.0, v2
	v_cmp_gt_f32_e32 vcc, s10, v1
	s_mov_b32 s24, 0x3f317217
	s_nop 0
	v_cndmask_b32_e64 v2, 0, 32, vcc
	v_ldexp_f32 v1, v1, v2
	v_log_f32_e32 v1, v1
	s_nop 0
	v_mul_f32_e32 v2, 0x3f317217, v1
	v_fma_f32 v2, v1, s24, -v2
	v_fmac_f32_e32 v2, 0x3377d1cf, v1
	s_mov_b32 s24, 0x7f800000
	v_fmac_f32_e32 v2, 0x3f317217, v1
	v_cmp_lt_f32_e64 s[24:25], |v1|, s24
	s_nop 1
	v_cndmask_b32_e64 v1, v1, v2, s[24:25]
	v_mov_b32_e32 v2, 0x41b17218
	v_cndmask_b32_e32 v2, 0, v2, vcc
	v_sub_f32_e32 v1, v1, v2

; DI void gdn_intra(LAS unsigned char* lds, PP p, int l, int first, int stride) {
;     ...
;         const float beta = 1.f / (1.f + __expf(-bl));
;         const float xx = al + p->in[17][l * 8 + hd];
;         const float ex = __expf(fminf(xx, 20.f));
;         const float sp = xx > 20.f ? xx : (ex < 0.05f ? ex * (1.f - ex * (0.5f - ex * (0.33333333f - ex * 0.25f))) : __logf(1.f + ex));
;         float gc = -__expf(p->in[16][l * 8 + hd]) * sp;
; #pragma unroll
;         for (int off = 1; off < 64; off <<= 1) { const float t = __shfl_up(gc, off); if (tid >= off) gc += t; }
;         const float gl = __shfl(gc, 63);
;         scb[tid] = beta; scg[tid] = gc; sce[tid] = __expf(gc); scl[tid] = __expf(gl - gc);
;         if (tid == 0) ((float*)(p->ws + O_GL))[hd * 256 + n] = __expf(gl);
.LBB0_428:
	s_or_b64 exec, exec, s[26:27]
	v_mul_f32_e32 v2, 0xbfb8aa3b, v135
	v_exp_f32_e32 v2, v2
	s_nop 0
	v_add_f32_e32 v2, 1.0, v2
	v_rcp_f32_e32 v5, v2
	s_nop 0
	v_mul_f32_e32 v7, 1.0, v5
	v_fma_f32 v8, -v2, v7, 1.0
	v_fmac_f32_e32 v7, v8, v5
	v_div_fixup_f32 v2, v7, v2, 1.0
	v_and_b32_e32 v6, 64, v220
	v_add_u32_e32 v7, -1, v220
	v_cmp_lt_i32_e32 vcc, v7, v6
	s_waitcnt lgkmcnt(0)
	v_mov_b32_e32 v4, s21
	v_mul_f32_e32 v4, 0x3fb8aa3b, v4
	v_exp_f32_e32 v4, v4
	v_cndmask_b32_e32 v7, v7, v220, vcc
	v_lshlrev_b32_e32 v7, 2, v7
	v_cmp_gt_i32_e32 vcc, 1, v138
	v_mul_f32_e64 v5, v1, -v4
	ds_bpermute_b32 v7, v7, v5
	s_waitcnt lgkmcnt(0)
	v_fma_f32 v1, v1, -v4, v7
	v_add_u32_e32 v4, -2, v220
	v_cndmask_b32_e32 v1, v1, v5, vcc
	v_cmp_lt_i32_e32 vcc, v4, v6
	v_lshlrev_b32_e32 v5, 2, v138
	s_nop 0
	v_cndmask_b32_e32 v4, v4, v220, vcc
	v_lshlrev_b32_e32 v4, 2, v4
	ds_bpermute_b32 v4, v4, v1
	v_cmp_gt_i32_e32 vcc, 2, v138
	s_waitcnt lgkmcnt(0)
	v_add_f32_e32 v4, v1, v4
	v_cndmask_b32_e32 v1, v4, v1, vcc
	v_add_u32_e32 v4, -4, v220
	v_cmp_lt_i32_e32 vcc, v4, v6
	s_nop 1
	v_cndmask_b32_e32 v4, v4, v220, vcc
	v_lshlrev_b32_e32 v4, 2, v4
	ds_bpermute_b32 v4, v4, v1
	v_cmp_gt_i32_e32 vcc, 4, v138
	s_waitcnt lgkmcnt(0)
	v_add_f32_e32 v4, v1, v4
	v_cndmask_b32_e32 v1, v4, v1, vcc
	v_add_u32_e32 v4, -8, v220
	v_cmp_lt_i32_e32 vcc, v4, v6
	s_nop 1
	v_cndmask_b32_e32 v4, v4, v220, vcc
	v_lshlrev_b32_e32 v4, 2, v4
	ds_bpermute_b32 v4, v4, v1
	v_cmp_gt_i32_e32 vcc, 8, v138
	s_waitcnt lgkmcnt(0)
	v_add_f32_e32 v4, v1, v4
	v_cndmask_b32_e32 v1, v4, v1, vcc
	v_add_u32_e32 v4, -16, v220
	v_cmp_lt_i32_e32 vcc, v4, v6
	s_nop 1
	v_cndmask_b32_e32 v4, v4, v220, vcc
	v_lshlrev_b32_e32 v4, 2, v4
	ds_bpermute_b32 v4, v4, v1
	v_cmp_gt_i32_e32 vcc, 16, v138
	s_waitcnt lgkmcnt(0)
	v_add_f32_e32 v4, v1, v4
	v_cndmask_b32_e32 v1, v4, v1, vcc
	v_subrev_u32_e32 v4, 32, v220
	v_cmp_lt_i32_e32 vcc, v4, v6
	v_add_u32_e32 v6, v23, v5
	ds_write_b32 v6, v2
	v_cndmask_b32_e32 v4, v4, v220, vcc
	v_lshlrev_b32_e32 v4, 2, v4
	ds_bpermute_b32 v4, v4, v1
	v_cmp_gt_i32_e32 vcc, 32, v138
	v_add_u32_e32 v2, v22, v5
	v_add_u32_e32 v6, v35, v5
	s_waitcnt lgkmcnt(0)
	v_add_f32_e32 v4, v1, v4
	v_cndmask_b32_e32 v4, v4, v1, vcc
	v_bfrev_b32_e32 v1, 0.5
	v_lshl_or_b32 v1, v220, 2, v1
	ds_bpermute_b32 v1, v1, v4
	ds_write_b32 v2, v4
	v_mul_f32_e32 v2, 0x3fb8aa3b, v4
	v_exp_f32_e32 v2, v2
	v_cmp_eq_u32_e32 vcc, 0, v138
	ds_write_b32 v6, v2
	s_waitcnt lgkmcnt(2)
	v_sub_f32_e32 v2, v1, v4
	v_mul_f32_e32 v2, 0x3fb8aa3b, v2
	v_exp_f32_e32 v2, v2
	v_add_u32_e32 v4, v30, v5
	ds_write_b32 v4, v2
	s_and_b64 exec, exec, vcc
	s_cbranch_execz .LBB0_430
	v_mul_f32_e32 v1, 0x3fb8aa3b, v1
	v_exp_f32_e32 v1, v1
	s_lshl_b64 s[20:21], s[54:55], 2
	s_add_u32 s20, s82, s20
	s_addc_u32 s21, s83, s21
	global_store_dword v3, v1, s[20:21]
